# layer-1 weight conversion segment after LRU-in dealt over all 256 workgroups (first idle block 64 -> 0)
# speedup vs baseline: 1.0009x; 1.0009x over previous
.LBB0_122:
	v_readlane_b32 s2, v244, 15
	v_readlane_b32 s3, v244, 16
	s_andn2_b64 vcc, exec, s[2:3]
	s_cbranch_vccnz .LBB0_146
	v_mov_b32_e32 v3, v180
	v_readlane_b32 s2, v246, 0
	s_cmp_lt_i32 s2, 0
	s_cbranch_scc1 .LBB0_146
	v_ashrrev_i32_e32 v20, 6, v3
	v_lshl_add_u32 v0, s2, 3, v20
	v_add_u32_e32 v15, 0, v0
	v_cmp_lt_i32_e32 vcc, -1, v15
	s_and_saveexec_b64 s[30:31], vcc
	s_cbranch_execz .LBB0_145
	s_add_u32 s34, s12, 0x100000
	v_and_b32_e32 v10, 63, v3
	s_addc_u32 s35, s13, 0
	s_add_u32 s36, s12, 0x3b00000
	s_movk_i32 s3, 0x800
	v_lshrrev_b32_e32 v16, 5, v10
	v_lshrrev_b32_e32 v11, 3, v10
	v_lshlrev_b32_e32 v0, 3, v10
	v_lshl_add_u32 v1, v20, 14, 0
	s_addc_u32 s37, s13, 0
	v_cmp_gt_u32_e32 vcc, s3, v15
	v_and_b32_e32 v2, 31, v3
	v_mul_u32_u24_e32 v14, 0x84, v16
	v_and_b32_e32 v0, 56, v0
	v_lshlrev_b32_e32 v13, 2, v11
	v_or_b32_e32 v12, 8, v11
	v_or_b32_e32 v17, 24, v11
	v_or_b32_e32 v18, 16, v11
	s_and_saveexec_b64 s[38:39], vcc
	s_cbranch_execz .LBB0_132
	v_add_u32_e32 v21, 0x4040, v15
	v_lshl_add_u32 v4, v2, 2, v1
	v_mul_u32_u24_e32 v5, 0x84, v0
	v_add3_u32 v19, v1, v5, v13
	v_lshlrev_b32_e32 v22, 5, v21
	s_mov_b64 s[40:41], 0
	v_add_u32_e32 v23, v4, v14
	s_branch .LBB0_128
.LBB0_127:
	s_or_b64 exec, exec, s[4:5]
	s_movk_i32 s3, 0x403f
	v_add_u32_e32 v4, 0x800, v21
	v_cmp_lt_i32_e32 vcc, s3, v21
	v_add_u32_e32 v22, 0x10000, v22
	s_or_b64 s[40:41], vcc, s[40:41]
	v_mov_b32_e32 v21, v4
	s_andn2_b64 exec, exec, s[40:41]
	s_cbranch_execz .LBB0_132

.LBB0_134:
	s_or_b64 exec, exec, s[4:5]
	s_movk_i32 s2, 0x603f
	v_add_u32_e32 v4, 0x800, v9
	v_cmp_lt_i32_e32 vcc, s2, v9
	v_add_u32_e32 v20, 0x10000, v20
	s_or_b64 s[40:41], vcc, s[40:41]
	v_mov_b32_e32 v9, v4
	s_andn2_b64 exec, exec, s[40:41]
	s_cbranch_execz .LBB0_143
.LBB0_135:
	s_movk_i32 s2, 0x383f
	v_cmp_lt_i32_e32 vcc, s2, v9
	s_and_saveexec_b64 s[2:3], vcc
	s_xor_b64 s[52:53], exec, s[2:3]
	s_cbranch_execz .LBB0_141
	s_movk_i32 s2, 0x483f
	v_cmp_lt_u32_e32 vcc, s2, v9
	s_and_saveexec_b64 s[2:3], vcc
	s_xor_b64 s[4:5], exec, s[2:3]
	s_cbranch_execz .LBB0_138
	v_add_u32_e32 v21, 0xffffb7c0, v9
	v_lshrrev_b32_e32 v144, 12, v21
	v_lshrrev_b32_e32 v21, 1, v21
	v_and_b32_e32 v24, 0x7c0, v21
	v_add_u32_e32 v21, 0x20000, v20
	v_lshlrev_b64 v[4:5], 25, v[144:145]
	v_and_b32_e32 v21, 0xfe0, v21
	v_lshl_add_u64 v[6:7], s[26:27], 0, v[4:5]
	v_lshlrev_b64 v[4:5], 24, v[144:145]
	v_lshlrev_b32_e32 v144, 2, v21
	v_or_b32_e32 v22, v24, v16
	v_lshl_add_u64 v[6:7], v[6:7], 0, v[144:145]
	v_lshlrev_b32_e32 v144, 2, v2
	v_lshl_add_u64 v[6:7], v[6:7], 0, v[144:145]
	v_lshlrev_b32_e32 v144, 14, v22
	v_lshl_add_u64 v[6:7], v[6:7], 0, v[144:145]
	s_mov_b32 s2, 0x8000
	v_add_co_u32_e32 v22, vcc, s2, v6
	s_mov_b32 s2, 0x10000
	s_nop 0
	v_addc_co_u32_e32 v23, vcc, 0, v7, vcc
	flat_load_dword v25, v[6:7]
	flat_load_dword v26, v[22:23]
	v_add_co_u32_e32 v22, vcc, s2, v6
	s_mov_b32 s2, 0x20000
	s_nop 0
	v_addc_co_u32_e32 v23, vcc, 0, v7, vcc
	flat_load_dword v27, v[22:23]
	v_add_co_u32_e32 v22, vcc, s89, v6
	v_lshlrev_b32_e32 v144, 1, v24
	s_nop 0
	v_addc_co_u32_e32 v23, vcc, 0, v7, vcc
	flat_load_dword v28, v[22:23]
	v_add_co_u32_e32 v22, vcc, s2, v6
	s_mov_b32 s2, 0x28000
	s_nop 0
	v_addc_co_u32_e32 v23, vcc, 0, v7, vcc
	flat_load_dword v29, v[22:23]
	v_add_co_u32_e32 v22, vcc, s2, v6
	s_mov_b32 s2, 0x30000
	s_nop 0
	v_addc_co_u32_e32 v23, vcc, 0, v7, vcc
	flat_load_dword v30, v[22:23]
	v_add_co_u32_e32 v22, vcc, s2, v6
	s_mov_b32 s2, 0x38000
	s_nop 0
	v_addc_co_u32_e32 v23, vcc, 0, v7, vcc
	flat_load_dword v31, v[22:23]
	v_add_co_u32_e32 v22, vcc, s2, v6
	s_mov_b32 s2, 0x40000
	s_nop 0
	v_addc_co_u32_e32 v23, vcc, 0, v7, vcc
	flat_load_dword v32, v[22:23]
	v_add_co_u32_e32 v22, vcc, s2, v6
	s_mov_b32 s2, 0x48000
	s_nop 0
	v_addc_co_u32_e32 v23, vcc, 0, v7, vcc
	flat_load_dword v33, v[22:23]
	v_add_co_u32_e32 v22, vcc, s2, v6
	s_mov_b32 s2, 0x50000
	s_nop 0
	v_addc_co_u32_e32 v23, vcc, 0, v7, vcc
	flat_load_dword v34, v[22:23]
	v_add_co_u32_e32 v22, vcc, s2, v6
	s_mov_b32 s2, 0x58000
	s_nop 0
	v_addc_co_u32_e32 v23, vcc, 0, v7, vcc
	flat_load_dword v35, v[22:23]
	v_add_co_u32_e32 v22, vcc, s2, v6
	s_mov_b32 s2, 0x60000
	s_nop 0
	v_addc_co_u32_e32 v23, vcc, 0, v7, vcc
	flat_load_dword v36, v[22:23]
	v_add_co_u32_e32 v22, vcc, s2, v6
	s_mov_b32 s2, 0x68000
	s_nop 0
	v_addc_co_u32_e32 v23, vcc, 0, v7, vcc
	flat_load_dword v37, v[22:23]
	v_add_co_u32_e32 v22, vcc, s2, v6
	s_mov_b32 s2, 0x70000
	s_nop 0
	v_addc_co_u32_e32 v23, vcc, 0, v7, vcc
	flat_load_dword v38, v[22:23]
	v_add_co_u32_e32 v22, vcc, s2, v6
	s_mov_b32 s2, 0x78000
	s_nop 0
	v_addc_co_u32_e32 v23, vcc, 0, v7, vcc
	flat_load_dword v39, v[22:23]
	v_add_co_u32_e32 v22, vcc, s2, v6
	s_mov_b32 s2, 0x80000
	s_nop 0
	v_addc_co_u32_e32 v23, vcc, 0, v7, vcc
	flat_load_dword v40, v[22:23]
	v_add_co_u32_e32 v22, vcc, s2, v6
	s_mov_b32 s2, 0x88000
	s_nop 0
	v_addc_co_u32_e32 v23, vcc, 0, v7, vcc
	flat_load_dword v41, v[22:23]
	v_add_co_u32_e32 v22, vcc, s2, v6
	s_mov_b32 s2, 0x90000
	s_nop 0
	v_addc_co_u32_e32 v23, vcc, 0, v7, vcc
	flat_load_dword v42, v[22:23]
	v_add_co_u32_e32 v22, vcc, s2, v6
	s_mov_b32 s2, 0x98000
	s_nop 0
	v_addc_co_u32_e32 v23, vcc, 0, v7, vcc
	flat_load_dword v43, v[22:23]
	v_add_co_u32_e32 v22, vcc, s2, v6
	s_mov_b32 s2, 0xa0000
	s_nop 0
	v_addc_co_u32_e32 v23, vcc, 0, v7, vcc
	flat_load_dword v44, v[22:23]
	v_add_co_u32_e32 v22, vcc, s2, v6
	s_mov_b32 s2, 0xa8000
	s_nop 0
	v_addc_co_u32_e32 v23, vcc, 0, v7, vcc
	flat_load_dword v45, v[22:23]
	v_add_co_u32_e32 v22, vcc, s2, v6
	s_mov_b32 s2, 0xb0000
	s_nop 0
	v_addc_co_u32_e32 v23, vcc, 0, v7, vcc
	flat_load_dword v46, v[22:23]
	v_add_co_u32_e32 v22, vcc, s2, v6
	s_mov_b32 s2, 0xb8000
	s_nop 0
	v_addc_co_u32_e32 v23, vcc, 0, v7, vcc
	flat_load_dword v47, v[22:23]
	v_add_co_u32_e32 v22, vcc, s2, v6
	s_mov_b32 s2, 0xc0000
	s_nop 0
	v_addc_co_u32_e32 v23, vcc, 0, v7, vcc
	flat_load_dword v48, v[22:23]
	v_add_co_u32_e32 v22, vcc, s2, v6
	s_mov_b32 s2, 0xc8000
	s_nop 0
	v_addc_co_u32_e32 v23, vcc, 0, v7, vcc
	flat_load_dword v49, v[22:23]
	v_add_co_u32_e32 v22, vcc, s2, v6
	s_mov_b32 s2, 0xd0000
	s_nop 0
	v_addc_co_u32_e32 v23, vcc, 0, v7, vcc
	flat_load_dword v50, v[22:23]
	v_add_co_u32_e32 v22, vcc, s2, v6
	s_mov_b32 s2, 0xd8000
	s_nop 0
	v_addc_co_u32_e32 v23, vcc, 0, v7, vcc
	flat_load_dword v51, v[22:23]
	v_add_co_u32_e32 v22, vcc, s2, v6
	s_mov_b32 s2, 0xe0000
	s_nop 0
	v_addc_co_u32_e32 v23, vcc, 0, v7, vcc
	flat_load_dword v52, v[22:23]
	v_add_co_u32_e32 v22, vcc, s2, v6
	s_mov_b32 s2, 0xe8000
	s_nop 0
	v_addc_co_u32_e32 v23, vcc, 0, v7, vcc
	flat_load_dword v53, v[22:23]
	v_add_co_u32_e32 v22, vcc, s2, v6
	s_mov_b32 s2, 0xf0000
	s_nop 0
	v_addc_co_u32_e32 v23, vcc, 0, v7, vcc
	flat_load_dword v54, v[22:23]
	v_add_co_u32_e32 v22, vcc, s2, v6
	s_mov_b32 s2, 0xf8000
	s_nop 0
	v_addc_co_u32_e32 v23, vcc, 0, v7, vcc
	v_add_co_u32_e32 v6, vcc, s2, v6
	flat_load_dword v22, v[22:23]
	s_nop 0
	v_addc_co_u32_e32 v7, vcc, 0, v7, vcc
	flat_load_dword v6, v[6:7]
	v_add_u32_e32 v7, 0x400, v8
	s_waitcnt vmcnt(0) lgkmcnt(0)
	ds_write2_b32 v8, v25, v26 offset1:66
	ds_write2_b32 v8, v27, v28 offset0:132 offset1:198
	ds_write2_b32 v7, v29, v30 offset0:8 offset1:74
	ds_write2_b32 v7, v31, v32 offset0:140 offset1:206
	v_add_u32_e32 v7, 0x800, v8
	ds_write2_b32 v7, v33, v34 offset0:16 offset1:82
	ds_write2_b32 v7, v35, v36 offset0:148 offset1:214
	v_add_u32_e32 v7, 0xc00, v8
	ds_write2_b32 v7, v37, v38 offset0:24 offset1:90
	ds_write2_b32 v7, v39, v40 offset0:156 offset1:222
	v_add_u32_e32 v7, 0x1000, v8
	ds_write2_b32 v7, v41, v42 offset0:32 offset1:98
	ds_write2_b32 v7, v43, v44 offset0:164 offset1:230
	v_add_u32_e32 v7, 0x1400, v8
	ds_write2_b32 v7, v45, v46 offset0:40 offset1:106
	ds_write2_b32 v7, v47, v48 offset0:172 offset1:238
	v_add_u32_e32 v7, 0x1800, v8
	ds_write2_b32 v7, v49, v50 offset0:48 offset1:114
	ds_write2_b32 v7, v51, v52 offset0:180 offset1:246
	v_add_u32_e32 v7, 0x1c00, v8
	ds_write2_b32 v7, v53, v54 offset0:56 offset1:122
	ds_write2_b32 v7, v22, v6 offset0:188 offset1:254
	s_waitcnt lgkmcnt(0)
	ds_read_b32 v6, v19
	ds_read_b32 v7, v19 offset:132
	v_lshl_add_u64 v[4:5], s[28:29], 0, v[4:5]
	v_lshl_add_u64 v[4:5], v[4:5], 0, v[144:145]
	v_lshlrev_b32_e32 v144, 1, v0
	s_waitcnt lgkmcnt(1)
	v_add_u32_e32 v6, 0x8000, v6
	s_waitcnt lgkmcnt(0)
	v_add_u32_e32 v7, 0x8000, v7
	v_perm_b32 v22, v7, v6, s81
	ds_read_b32 v6, v19 offset:264
	ds_read_b32 v7, v19 offset:396
	v_lshl_add_u64 v[4:5], v[4:5], 0, v[144:145]
	s_waitcnt lgkmcnt(1)
	v_add_u32_e32 v6, 0x8000, v6
	s_waitcnt lgkmcnt(0)
	v_add_u32_e32 v7, 0x8000, v7
	v_perm_b32 v23, v7, v6, s81
	ds_read_b32 v6, v19 offset:528
	ds_read_b32 v7, v19 offset:660
	s_waitcnt lgkmcnt(1)
	v_add_u32_e32 v6, 0x8000, v6
	s_waitcnt lgkmcnt(0)
	v_add_u32_e32 v7, 0x8000, v7
	v_perm_b32 v24, v7, v6, s81
	ds_read_b32 v6, v19 offset:792
	ds_read_b32 v7, v19 offset:924
	s_waitcnt lgkmcnt(1)
	v_add_u32_e32 v6, 0x8000, v6
	s_waitcnt lgkmcnt(0)
	v_add_u32_e32 v7, 0x8000, v7
	v_perm_b32 v25, v7, v6, s81
	v_or_b32_e32 v6, v21, v11
	v_lshlrev_b32_e32 v144, 12, v6
	v_lshl_add_u64 v[6:7], v[4:5], 0, v[144:145]
	flat_store_dwordx4 v[6:7], v[22:25]
	ds_read_b32 v6, v19 offset:32
	ds_read_b32 v7, v19 offset:164
	s_waitcnt lgkmcnt(0)
	v_add_u32_e32 v6, 0x8000, v6
	v_add_u32_e32 v7, 0x8000, v7
	v_perm_b32 v22, v7, v6, s81
	ds_read_b32 v6, v19 offset:296
	ds_read_b32 v7, v19 offset:428
	s_waitcnt lgkmcnt(0)
	v_add_u32_e32 v6, 0x8000, v6
	v_add_u32_e32 v7, 0x8000, v7
	v_perm_b32 v23, v7, v6, s81
	ds_read_b32 v6, v19 offset:560
	ds_read_b32 v7, v19 offset:692
	s_waitcnt lgkmcnt(0)
	v_add_u32_e32 v6, 0x8000, v6
	v_add_u32_e32 v7, 0x8000, v7
	v_perm_b32 v24, v7, v6, s81
	ds_read_b32 v6, v19 offset:824
	ds_read_b32 v7, v19 offset:956
	s_waitcnt lgkmcnt(0)
	v_add_u32_e32 v6, 0x8000, v6
	v_add_u32_e32 v7, 0x8000, v7
	v_perm_b32 v25, v7, v6, s81
	v_or_b32_e32 v6, v21, v12
	v_lshlrev_b32_e32 v144, 12, v6
	v_lshl_add_u64 v[6:7], v[4:5], 0, v[144:145]
	flat_store_dwordx4 v[6:7], v[22:25]
	ds_read_b32 v6, v19 offset:64
	ds_read_b32 v7, v19 offset:196
	s_waitcnt lgkmcnt(0)
	v_add_u32_e32 v6, 0x8000, v6
	v_add_u32_e32 v7, 0x8000, v7
	v_perm_b32 v22, v7, v6, s81
	ds_read_b32 v6, v19 offset:328
	ds_read_b32 v7, v19 offset:460
	s_waitcnt lgkmcnt(0)
	v_add_u32_e32 v6, 0x8000, v6
	v_add_u32_e32 v7, 0x8000, v7
	v_perm_b32 v23, v7, v6, s81
	ds_read_b32 v6, v19 offset:592
	ds_read_b32 v7, v19 offset:724
	s_waitcnt lgkmcnt(0)
	v_add_u32_e32 v6, 0x8000, v6
	v_add_u32_e32 v7, 0x8000, v7
	v_perm_b32 v24, v7, v6, s81
	ds_read_b32 v6, v19 offset:856
	ds_read_b32 v7, v19 offset:988
	s_waitcnt lgkmcnt(0)
	v_add_u32_e32 v6, 0x8000, v6
	v_add_u32_e32 v7, 0x8000, v7
	v_perm_b32 v25, v7, v6, s81
	v_or_b32_e32 v6, v21, v18
	v_lshlrev_b32_e32 v144, 12, v6
	v_lshl_add_u64 v[6:7], v[4:5], 0, v[144:145]
	flat_store_dwordx4 v[6:7], v[22:25]
	ds_read_b32 v6, v19 offset:96
	ds_read_b32 v7, v19 offset:228
	s_waitcnt lgkmcnt(0)
	v_add_u32_e32 v6, 0x8000, v6
	v_add_u32_e32 v7, 0x8000, v7
	v_perm_b32 v22, v7, v6, s81
	ds_read_b32 v6, v19 offset:360
	ds_read_b32 v7, v19 offset:492
	s_waitcnt lgkmcnt(0)
	v_add_u32_e32 v6, 0x8000, v6
	v_add_u32_e32 v7, 0x8000, v7
	v_perm_b32 v23, v7, v6, s81
	ds_read_b32 v6, v19 offset:624
	ds_read_b32 v7, v19 offset:756
	s_waitcnt lgkmcnt(0)
	v_add_u32_e32 v6, 0x8000, v6
	v_add_u32_e32 v7, 0x8000, v7
	v_perm_b32 v24, v7, v6, s81
	ds_read_b32 v6, v19 offset:888
	ds_read_b32 v7, v19 offset:1020
	s_waitcnt lgkmcnt(0)
	v_add_u32_e32 v6, 0x8000, v6
	v_add_u32_e32 v7, 0x8000, v7
	v_perm_b32 v25, v7, v6, s81
	v_or_b32_e32 v6, v21, v17
	v_lshlrev_b32_e32 v144, 12, v6
	v_lshl_add_u64 v[4:5], v[4:5], 0, v[144:145]
	flat_store_dwordx4 v[4:5], v[22:25]
	s_waitcnt lgkmcnt(0)
.LBB0_138:
	s_or_saveexec_b64 s[4:5], s[4:5]
	s_mov_b32 s3, 0x14000
	s_xor_b64 exec, exec, s[4:5]
	s_cbranch_execz .LBB0_140
	v_add_u32_e32 v21, 0xffffc7c0, v9
	v_and_b32_e32 v144, 0xfffff800, v21
	v_and_b32_e32 v24, 0x7c0, v21
	v_add_u32_e32 v21, 0xb0800, v20
	v_lshlrev_b64 v[4:5], 13, v[144:145]
	v_and_b32_e32 v21, 0x7e0, v21
	v_lshl_add_u64 v[6:7], s[16:17], 0, v[4:5]
	v_lshlrev_b64 v[4:5], 12, v[144:145]
	v_lshlrev_b32_e32 v144, 2, v21
	v_or_b32_e32 v22, v24, v16
	v_lshl_add_u64 v[6:7], v[6:7], 0, v[144:145]
	v_lshlrev_b32_e32 v144, 2, v2
	v_lshl_add_u64 v[6:7], v[6:7], 0, v[144:145]
	v_lshlrev_b32_e32 v144, 13, v22
	v_lshl_add_u64 v[6:7], v[6:7], 0, v[144:145]
	s_movk_i32 s2, 0x4000
	v_add_co_u32_e32 v22, vcc, s2, v6
	s_mov_b32 s2, 0x8000
	s_nop 0
	v_addc_co_u32_e32 v23, vcc, 0, v7, vcc
	flat_load_dword v25, v[6:7]
	flat_load_dword v26, v[22:23]
	v_add_co_u32_e32 v22, vcc, s2, v6
	s_mov_b32 s2, 0xc000
	s_nop 0
	v_addc_co_u32_e32 v23, vcc, 0, v7, vcc
	flat_load_dword v27, v[22:23]
	v_add_co_u32_e32 v22, vcc, s2, v6
	s_mov_b32 s2, 0x10000
	s_nop 0
	v_addc_co_u32_e32 v23, vcc, 0, v7, vcc
	flat_load_dword v28, v[22:23]
	v_add_co_u32_e32 v22, vcc, s2, v6
	s_mov_b32 s2, 0x1c000
	s_nop 0
	v_addc_co_u32_e32 v23, vcc, 0, v7, vcc
	flat_load_dword v29, v[22:23]
	v_add_co_u32_e32 v22, vcc, s3, v6
	v_lshlrev_b32_e32 v144, 1, v24
	s_nop 0
	v_addc_co_u32_e32 v23, vcc, 0, v7, vcc
	flat_load_dword v30, v[22:23]
	v_add_co_u32_e32 v22, vcc, s89, v6
	v_lshl_add_u64 v[4:5], s[36:37], 0, v[4:5]
	s_nop 0
	v_addc_co_u32_e32 v23, vcc, 0, v7, vcc
	flat_load_dword v31, v[22:23]
	v_add_co_u32_e32 v22, vcc, s2, v6
	s_mov_b32 s2, 0x20000
	s_nop 0
	v_addc_co_u32_e32 v23, vcc, 0, v7, vcc
	flat_load_dword v32, v[22:23]
	v_add_co_u32_e32 v22, vcc, s2, v6
	s_mov_b32 s2, 0x24000
	s_nop 0
	v_addc_co_u32_e32 v23, vcc, 0, v7, vcc
	flat_load_dword v33, v[22:23]
	v_add_co_u32_e32 v22, vcc, s2, v6
	s_mov_b32 s2, 0x28000
	s_nop 0
	v_addc_co_u32_e32 v23, vcc, 0, v7, vcc
	flat_load_dword v34, v[22:23]
	v_add_co_u32_e32 v22, vcc, s2, v6
	s_mov_b32 s2, 0x2c000
	s_nop 0
	v_addc_co_u32_e32 v23, vcc, 0, v7, vcc
	flat_load_dword v35, v[22:23]
	v_add_co_u32_e32 v22, vcc, s2, v6
	s_mov_b32 s2, 0x30000
	s_nop 0
	v_addc_co_u32_e32 v23, vcc, 0, v7, vcc
	flat_load_dword v36, v[22:23]
	v_add_co_u32_e32 v22, vcc, s2, v6
	s_mov_b32 s2, 0x34000
	s_nop 0
	v_addc_co_u32_e32 v23, vcc, 0, v7, vcc
	flat_load_dword v37, v[22:23]
	v_add_co_u32_e32 v22, vcc, s2, v6
	s_mov_b32 s2, 0x38000
	s_nop 0
	v_addc_co_u32_e32 v23, vcc, 0, v7, vcc
	flat_load_dword v38, v[22:23]
	v_add_co_u32_e32 v22, vcc, s2, v6
	s_mov_b32 s2, 0x3c000
	s_nop 0
	v_addc_co_u32_e32 v23, vcc, 0, v7, vcc
	flat_load_dword v39, v[22:23]
	v_add_co_u32_e32 v22, vcc, s2, v6
	s_mov_b32 s2, 0x40000
	s_nop 0
	v_addc_co_u32_e32 v23, vcc, 0, v7, vcc
	flat_load_dword v40, v[22:23]
	v_add_co_u32_e32 v22, vcc, s2, v6
	s_mov_b32 s2, 0x44000
	s_nop 0
	v_addc_co_u32_e32 v23, vcc, 0, v7, vcc
	flat_load_dword v41, v[22:23]
	v_add_co_u32_e32 v22, vcc, s2, v6
	s_mov_b32 s2, 0x48000
	s_nop 0
	v_addc_co_u32_e32 v23, vcc, 0, v7, vcc
	flat_load_dword v42, v[22:23]
	v_add_co_u32_e32 v22, vcc, s2, v6
	s_mov_b32 s2, 0x4c000
	s_nop 0
	v_addc_co_u32_e32 v23, vcc, 0, v7, vcc
	flat_load_dword v43, v[22:23]
	v_add_co_u32_e32 v22, vcc, s2, v6
	s_mov_b32 s2, 0x50000
	s_nop 0
	v_addc_co_u32_e32 v23, vcc, 0, v7, vcc
	flat_load_dword v44, v[22:23]
	v_add_co_u32_e32 v22, vcc, s2, v6
	s_mov_b32 s2, 0x54000
	s_nop 0
	v_addc_co_u32_e32 v23, vcc, 0, v7, vcc
	flat_load_dword v45, v[22:23]
	v_add_co_u32_e32 v22, vcc, s2, v6
	s_mov_b32 s2, 0x58000
	s_nop 0
	v_addc_co_u32_e32 v23, vcc, 0, v7, vcc
	flat_load_dword v46, v[22:23]
	v_add_co_u32_e32 v22, vcc, s2, v6
	s_mov_b32 s2, 0x5c000
	s_nop 0
	v_addc_co_u32_e32 v23, vcc, 0, v7, vcc
	flat_load_dword v47, v[22:23]
	v_add_co_u32_e32 v22, vcc, s2, v6
	s_mov_b32 s2, 0x60000
	s_nop 0
	v_addc_co_u32_e32 v23, vcc, 0, v7, vcc
	flat_load_dword v48, v[22:23]
	v_add_co_u32_e32 v22, vcc, s2, v6
	s_mov_b32 s2, 0x64000
	s_nop 0
	v_addc_co_u32_e32 v23, vcc, 0, v7, vcc
	flat_load_dword v49, v[22:23]
	v_add_co_u32_e32 v22, vcc, s2, v6
	s_mov_b32 s2, 0x68000
	s_nop 0
	v_addc_co_u32_e32 v23, vcc, 0, v7, vcc
	flat_load_dword v50, v[22:23]
	v_add_co_u32_e32 v22, vcc, s2, v6
	s_mov_b32 s2, 0x6c000
	s_nop 0
	v_addc_co_u32_e32 v23, vcc, 0, v7, vcc
	flat_load_dword v51, v[22:23]
	v_add_co_u32_e32 v22, vcc, s2, v6
	s_mov_b32 s2, 0x70000
	s_nop 0
	v_addc_co_u32_e32 v23, vcc, 0, v7, vcc
	flat_load_dword v52, v[22:23]
	v_add_co_u32_e32 v22, vcc, s2, v6
	s_mov_b32 s2, 0x74000
	s_nop 0
	v_addc_co_u32_e32 v23, vcc, 0, v7, vcc
	flat_load_dword v53, v[22:23]
	v_add_co_u32_e32 v22, vcc, s2, v6
	s_mov_b32 s2, 0x78000
	s_nop 0
	v_addc_co_u32_e32 v23, vcc, 0, v7, vcc
	flat_load_dword v54, v[22:23]
	v_add_co_u32_e32 v22, vcc, s2, v6
	s_mov_b32 s2, 0x7c000
	s_nop 0
	v_addc_co_u32_e32 v23, vcc, 0, v7, vcc
	v_add_co_u32_e32 v6, vcc, s2, v6
	flat_load_dword v22, v[22:23]
	s_nop 0
	v_addc_co_u32_e32 v7, vcc, 0, v7, vcc
	flat_load_dword v6, v[6:7]
	v_add_u32_e32 v7, 0x400, v8
	s_waitcnt vmcnt(0) lgkmcnt(0)
	ds_write2_b32 v8, v25, v26 offset1:66
	ds_write2_b32 v8, v27, v28 offset0:132 offset1:198
	ds_write2_b32 v7, v29, v30 offset0:8 offset1:74
	ds_write2_b32 v7, v31, v32 offset0:140 offset1:206
	v_add_u32_e32 v7, 0x800, v8
	ds_write2_b32 v7, v33, v34 offset0:16 offset1:82
	ds_write2_b32 v7, v35, v36 offset0:148 offset1:214
	v_add_u32_e32 v7, 0xc00, v8
	ds_write2_b32 v7, v37, v38 offset0:24 offset1:90
	ds_write2_b32 v7, v39, v40 offset0:156 offset1:222
	v_add_u32_e32 v7, 0x1000, v8
	ds_write2_b32 v7, v41, v42 offset0:32 offset1:98
	ds_write2_b32 v7, v43, v44 offset0:164 offset1:230
	v_add_u32_e32 v7, 0x1400, v8
	ds_write2_b32 v7, v45, v46 offset0:40 offset1:106
	ds_write2_b32 v7, v47, v48 offset0:172 offset1:238
	v_add_u32_e32 v7, 0x1800, v8
	ds_write2_b32 v7, v49, v50 offset0:48 offset1:114
	ds_write2_b32 v7, v51, v52 offset0:180 offset1:246
	v_add_u32_e32 v7, 0x1c00, v8
	ds_write2_b32 v7, v53, v54 offset0:56 offset1:122
	ds_write2_b32 v7, v22, v6 offset0:188 offset1:254
	s_waitcnt lgkmcnt(0)
	ds_read_b32 v6, v19
	ds_read_b32 v7, v19 offset:132
	v_lshl_add_u64 v[4:5], v[4:5], 0, v[144:145]
	v_lshlrev_b32_e32 v144, 1, v0
	v_lshl_add_u64 v[4:5], v[4:5], 0, v[144:145]
	s_waitcnt lgkmcnt(1)
	v_add_u32_e32 v6, 0x8000, v6
	s_waitcnt lgkmcnt(0)
	v_add_u32_e32 v7, 0x8000, v7
	v_perm_b32 v22, v7, v6, s81
	ds_read_b32 v6, v19 offset:264
	ds_read_b32 v7, v19 offset:396
	s_waitcnt lgkmcnt(1)
	v_add_u32_e32 v6, 0x8000, v6
	s_waitcnt lgkmcnt(0)
	v_add_u32_e32 v7, 0x8000, v7
	v_perm_b32 v23, v7, v6, s81
	ds_read_b32 v6, v19 offset:528
	ds_read_b32 v7, v19 offset:660
	s_waitcnt lgkmcnt(1)
	v_add_u32_e32 v6, 0x8000, v6
	s_waitcnt lgkmcnt(0)
	v_add_u32_e32 v7, 0x8000, v7
	v_perm_b32 v24, v7, v6, s81
	ds_read_b32 v6, v19 offset:792
	ds_read_b32 v7, v19 offset:924
	s_waitcnt lgkmcnt(1)
	v_add_u32_e32 v6, 0x8000, v6
	s_waitcnt lgkmcnt(0)
	v_add_u32_e32 v7, 0x8000, v7
	v_perm_b32 v25, v7, v6, s81
	v_or_b32_e32 v6, v21, v11
	v_lshlrev_b32_e32 v144, 12, v6
	v_lshl_add_u64 v[6:7], v[4:5], 0, v[144:145]
	flat_store_dwordx4 v[6:7], v[22:25]
	ds_read_b32 v6, v19 offset:32
	ds_read_b32 v7, v19 offset:164
	s_waitcnt lgkmcnt(0)
	v_add_u32_e32 v6, 0x8000, v6
	v_add_u32_e32 v7, 0x8000, v7
	v_perm_b32 v22, v7, v6, s81
	ds_read_b32 v6, v19 offset:296
	ds_read_b32 v7, v19 offset:428
	s_waitcnt lgkmcnt(0)
	v_add_u32_e32 v6, 0x8000, v6
	v_add_u32_e32 v7, 0x8000, v7
	v_perm_b32 v23, v7, v6, s81
	ds_read_b32 v6, v19 offset:560
	ds_read_b32 v7, v19 offset:692
	s_waitcnt lgkmcnt(0)
	v_add_u32_e32 v6, 0x8000, v6
	v_add_u32_e32 v7, 0x8000, v7
	v_perm_b32 v24, v7, v6, s81
	ds_read_b32 v6, v19 offset:824
	ds_read_b32 v7, v19 offset:956
	s_waitcnt lgkmcnt(0)
	v_add_u32_e32 v6, 0x8000, v6
	v_add_u32_e32 v7, 0x8000, v7
	v_perm_b32 v25, v7, v6, s81
	v_or_b32_e32 v6, v21, v12
	v_lshlrev_b32_e32 v144, 12, v6
	v_lshl_add_u64 v[6:7], v[4:5], 0, v[144:145]
	flat_store_dwordx4 v[6:7], v[22:25]
	ds_read_b32 v6, v19 offset:64
	ds_read_b32 v7, v19 offset:196
	s_waitcnt lgkmcnt(0)
	v_add_u32_e32 v6, 0x8000, v6
	v_add_u32_e32 v7, 0x8000, v7
	v_perm_b32 v22, v7, v6, s81
	ds_read_b32 v6, v19 offset:328
	ds_read_b32 v7, v19 offset:460
	s_waitcnt lgkmcnt(0)
	v_add_u32_e32 v6, 0x8000, v6
	v_add_u32_e32 v7, 0x8000, v7
	v_perm_b32 v23, v7, v6, s81
	ds_read_b32 v6, v19 offset:592
	ds_read_b32 v7, v19 offset:724
	s_waitcnt lgkmcnt(0)
	v_add_u32_e32 v6, 0x8000, v6
	v_add_u32_e32 v7, 0x8000, v7
	v_perm_b32 v24, v7, v6, s81
	ds_read_b32 v6, v19 offset:856
	ds_read_b32 v7, v19 offset:988
	s_waitcnt lgkmcnt(0)
	v_add_u32_e32 v6, 0x8000, v6
	v_add_u32_e32 v7, 0x8000, v7
	v_perm_b32 v25, v7, v6, s81
	v_or_b32_e32 v6, v21, v18
	v_lshlrev_b32_e32 v144, 12, v6
	v_lshl_add_u64 v[6:7], v[4:5], 0, v[144:145]
	flat_store_dwordx4 v[6:7], v[22:25]
	ds_read_b32 v6, v19 offset:96
	ds_read_b32 v7, v19 offset:228
	s_waitcnt lgkmcnt(0)
	v_add_u32_e32 v6, 0x8000, v6
	v_add_u32_e32 v7, 0x8000, v7
	v_perm_b32 v22, v7, v6, s81
	ds_read_b32 v6, v19 offset:360
	ds_read_b32 v7, v19 offset:492
	s_waitcnt lgkmcnt(0)
	v_add_u32_e32 v6, 0x8000, v6
	v_add_u32_e32 v7, 0x8000, v7
	v_perm_b32 v23, v7, v6, s81
	ds_read_b32 v6, v19 offset:624
	ds_read_b32 v7, v19 offset:756
	s_waitcnt lgkmcnt(0)
	v_add_u32_e32 v6, 0x8000, v6
	v_add_u32_e32 v7, 0x8000, v7
	v_perm_b32 v24, v7, v6, s81
	ds_read_b32 v6, v19 offset:888
	ds_read_b32 v7, v19 offset:1020
	s_waitcnt lgkmcnt(0)
	v_add_u32_e32 v6, 0x8000, v6
	v_add_u32_e32 v7, 0x8000, v7
	v_perm_b32 v25, v7, v6, s81
	v_or_b32_e32 v6, v21, v17
	v_lshlrev_b32_e32 v144, 12, v6
	v_lshl_add_u64 v[4:5], v[4:5], 0, v[144:145]
	flat_store_dwordx4 v[4:5], v[22:25]
	s_waitcnt lgkmcnt(0)
